# grid barrier after outproj/down replaced by per-panel counters (release: LDS-transposed full-row write-through X stores; acquire: poll + inv in the row-norm phase header)
# speedup vs baseline: 1.0225x; 1.0168x over previous
.LBB0_8:
	v_writelane_b32 v254, s78, 24
	s_mov_b32 s0, s49
	s_ashr_i32 s1, s0, 31
	v_writelane_b32 v254, s79, 25
	v_writelane_b32 v254, s76, 26
	v_readlane_b32 s2, v253, 3
	v_readlane_b32 s3, v253, 4
	v_writelane_b32 v254, s77, 27
	v_writelane_b32 v254, s74, 28
	s_add_u32 s0, s2, s0
	s_addc_u32 s1, s3, s1
	v_writelane_b32 v254, s75, 29
	v_writelane_b32 v254, s66, 30
	v_readlane_b32 s24, v253, 62
	v_writelane_b32 v254, s67, 31
	v_readlane_b32 s25, v253, 63
	s_load_dwordx16 s[52:67], s[0:1], 0x0
	s_load_dwordx2 s[30:31], s[0:1], 0x70
	s_load_dwordx4 s[36:39], s[0:1], 0x60
	s_load_dwordx8 s[12:19], s[0:1], 0x40
	s_load_dwordx2 s[2:3], s[0:1], 0x88
	s_load_dwordx8 s[68:75], s[0:1], 0x98
	s_load_dwordx16 s[80:95], s[0:1], 0xc0
	s_load_dwordx4 s[96:99], s[0:1], 0x120
	s_load_dwordx8 s[4:11], s[0:1], 0x100
	s_waitcnt lgkmcnt(0)
	s_movk_i32 s100, 0
	s_cmp_eq_u32 s46, 6
	s_cselect_b32 s100, 8, s100
	s_cmp_eq_u32 s46, 10
	s_cselect_b32 s100, 16, s100
	s_cmp_eq_u32 s46, 15
	s_cselect_b32 s100, 24, s100
	s_cmp_eq_u32 s46, 19
	s_cselect_b32 s100, 32, s100
	s_cmp_eq_u32 s100, 0
	s_cbranch_scc1 .Lpf_done
	v_lshrrev_b32_e32 v2, 6, v1
	s_nop 1
	v_readfirstlane_b32 s0, v2
	s_cmp_lg_u32 s0, 0
	s_cbranch_scc1 .Lpf_wait
	v_readlane_b32 s0, v253, 0
	s_lshr_b32 s1, s0, 4
	s_lshr_b32 s0, s0, 5
	s_cmp_eq_u32 s46, 19
	s_cselect_b32 s0, s0, s1
	s_cselect_b32 s1, 7, 15
	v_and_b32_e32 v2, s1, v194
	v_cmp_eq_u32_e32 vcc, s0, v2
	v_mov_b32_e32 v3, s100
	v_cndmask_b32_e32 v3, 0, v3, vcc
	v_cmp_gt_u32_e32 vcc, 32, v194
	v_cndmask_b32_e32 v3, 0, v3, vcc
	v_lshlrev_b32_e32 v2, 2, v194
	v_readlane_b32 s0, v253, 5
	v_readlane_b32 s1, v253, 6
	s_movk_i32 s100, 0x1000
	s_nop 4
.Lpf_poll:
	global_load_dword v4, v2, s[0:1] sc1
	s_waitcnt vmcnt(0)
	v_cmp_lt_u32_e32 vcc, v4, v3
	s_cbranch_vccz .Lpf_ok
	s_sleep 1
	s_add_i32 s100, s100, -1
	s_cmp_lg_u32 s100, 0
	s_cbranch_scc1 .Lpf_poll
.Lpf_ok:
	buffer_inv sc1
	s_waitcnt vmcnt(0)

.Lpf_done:
	v_writelane_b32 v254, s36, 32
	s_nop 1
	v_writelane_b32 v254, s37, 33
	v_writelane_b32 v254, s38, 34
	v_writelane_b32 v254, s39, 35
	v_writelane_b32 v254, s12, 36
	v_writelane_b32 v254, s13, 37
	v_writelane_b32 v254, s14, 38
	v_writelane_b32 v254, s15, 39
	v_writelane_b32 v254, s16, 40
	v_writelane_b32 v254, s17, 41
	v_writelane_b32 v254, s18, 42
	v_writelane_b32 v254, s19, 43
	v_writelane_b32 v254, s80, 44
	v_writelane_b32 v254, s81, 45
	v_writelane_b32 v254, s82, 46
	v_writelane_b32 v254, s83, 47
	v_writelane_b32 v254, s84, 48
	v_writelane_b32 v254, s85, 49
	v_writelane_b32 v254, s86, 50
	v_writelane_b32 v254, s87, 51
	v_writelane_b32 v254, s88, 52
	v_writelane_b32 v254, s89, 53
	v_writelane_b32 v254, s90, 54
	v_writelane_b32 v254, s91, 55
	v_writelane_b32 v254, s92, 56
	v_writelane_b32 v254, s93, 57
	v_writelane_b32 v254, s94, 58
	v_writelane_b32 v254, s95, 59
	s_mov_b64 s[38:39], s[2:3]
	s_mov_b64 s[36:37], 0x800
	s_mov_b64 s[2:3], 0
	s_mov_b32 s14, s90
	s_mov_b32 s15, s91
	s_mov_b32 s16, s92
	s_mov_b32 s17, s93
	s_mov_b64 s[12:13], -1
	s_mov_b64 s[0:1], 0
	s_mov_b32 s18, 0x800000
	s_movk_i32 s19, 0x1fff
	s_cmp_lt_i32 s46, 19
	s_cbranch_scc1 .LBB0_15
	s_cmp_eq_u32 s46, 19
	s_mov_b64 s[0:1], -1
	s_cbranch_scc0 .LBB0_14
	v_readlane_b32 s0, v253, 0
	v_mov_b32_e32 v2, v1
	s_lshl_b32 s12, s0, 3
	v_ashrrev_i32_e32 v2, 6, v2
	v_add_u32_e32 v6, s12, v2
	s_movk_i32 s0, 0x2000
	v_cmp_gt_i32_e32 vcc, s0, v6
	s_and_saveexec_b64 s[0:1], vcc
	v_readlane_b32 s16, v254, 6
	v_readlane_b32 s17, v254, 7
	s_cbranch_execz .LBB0_13
	v_ashrrev_i32_e32 v3, 31, v2
	s_ashr_i32 s13, s12, 31
	v_lshl_add_u64 v[4:5], v[2:3], 0, s[12:13]
	v_lshlrev_b64 v[2:3], 11, v[4:5]
	v_lshlrev_b64 v[4:5], 12, v[4:5]
	v_lshl_add_u64 v[4:5], s[70:71], 0, v[4:5]
	v_lshl_add_u64 v[2:3], s[74:75], 0, v[2:3]
	v_lshl_add_u64 v[4:5], v[4:5], 0, s[36:37]
	s_mov_b64 s[12:13], 0

.Ldn_join:
	s_waitcnt vmcnt(0)
	s_nop 7
	s_barrier
	s_mul_i32 s12, s76, 9
	v_and_b32_e32 v170, 15, v1
	v_bfe_u32 v171, v1, 4, 2
	v_mul_u32_u24_e32 v130, 0x90, v170
	v_lshl_add_u32 v130, v171, 3, v130
	v_add_u32_e32 v130, s12, v130
	v_bfe_u32 v170, v1, 3, 3
	v_and_b32_e32 v171, 7, v1
	v_mul_u32_u24_e32 v131, 0x90, v170
	v_lshl_add_u32 v131, v171, 4, v131
	v_add_u32_e32 v131, s12, v131
	v_lshrrev_b32_e32 v172, 7, v1
	v_lshl_add_u32 v170, v172, 6, v170
	v_lshlrev_b32_e32 v132, 11, v170
	v_lshl_add_u32 v132, v171, 4, v132
	v_bfe_u32 v172, v1, 6, 1
	v_lshl_add_u32 v132, v172, 7, v132
	v_lshlrev_b32_e32 v68, 16, v67
	v_and_b32_e32 v69, 0xffff0000, v67
	v_and_b32_e32 v67, 0xffff0000, v66
	v_lshlrev_b32_e32 v66, 16, v66
	v_pk_fma_f32 v[4:5], v[4:5], v[176:177], v[68:69]
	v_pk_fma_f32 v[2:3], v[2:3], v[174:175], v[66:67]
	s_nop 0
	v_cvt_pk_bf16_f32 v2, v2, v3
	v_cvt_pk_bf16_f32 v3, v4, v5
	ds_write_b64 v130, v[2:3] offset:0
	v_lshlrev_b32_e32 v72, 16, v71
	v_and_b32_e32 v73, 0xffff0000, v71
	v_and_b32_e32 v71, 0xffff0000, v70
	v_lshlrev_b32_e32 v70, 16, v70
	v_pk_fma_f32 v[8:9], v[8:9], v[180:181], v[72:73]
	v_pk_fma_f32 v[6:7], v[6:7], v[178:179], v[70:71]
	s_nop 0
	v_cvt_pk_bf16_f32 v6, v6, v7
	v_cvt_pk_bf16_f32 v7, v8, v9
	ds_write_b64 v130, v[6:7] offset:32
	v_lshlrev_b32_e32 v76, 16, v75
	v_and_b32_e32 v77, 0xffff0000, v75
	v_and_b32_e32 v75, 0xffff0000, v74
	v_lshlrev_b32_e32 v74, 16, v74
	v_pk_fma_f32 v[12:13], v[12:13], v[184:185], v[76:77]
	v_pk_fma_f32 v[10:11], v[10:11], v[182:183], v[74:75]
	s_nop 0
	v_cvt_pk_bf16_f32 v10, v10, v11
	v_cvt_pk_bf16_f32 v11, v12, v13
	ds_write_b64 v130, v[10:11] offset:64
	v_lshlrev_b32_e32 v80, 16, v79
	v_and_b32_e32 v81, 0xffff0000, v79
	v_and_b32_e32 v79, 0xffff0000, v78
	v_lshlrev_b32_e32 v78, 16, v78
	v_pk_fma_f32 v[16:17], v[16:17], v[188:189], v[80:81]
	v_pk_fma_f32 v[14:15], v[14:15], v[186:187], v[78:79]
	s_nop 0
	v_cvt_pk_bf16_f32 v14, v14, v15
	v_cvt_pk_bf16_f32 v15, v16, v17
	ds_write_b64 v130, v[14:15] offset:96
	v_lshlrev_b32_e32 v84, 16, v83
	v_and_b32_e32 v85, 0xffff0000, v83
	v_and_b32_e32 v83, 0xffff0000, v82
	v_lshlrev_b32_e32 v82, 16, v82
	v_pk_fma_f32 v[20:21], v[20:21], v[176:177], v[84:85]
	v_pk_fma_f32 v[18:19], v[18:19], v[174:175], v[82:83]
	s_nop 0
	v_cvt_pk_bf16_f32 v18, v18, v19
	v_cvt_pk_bf16_f32 v19, v20, v21
	ds_write_b64 v130, v[18:19] offset:2304
	v_lshlrev_b32_e32 v88, 16, v87
	v_and_b32_e32 v89, 0xffff0000, v87
	v_and_b32_e32 v87, 0xffff0000, v86
	v_lshlrev_b32_e32 v86, 16, v86
	v_pk_fma_f32 v[24:25], v[24:25], v[180:181], v[88:89]
	v_pk_fma_f32 v[22:23], v[22:23], v[178:179], v[86:87]
	s_nop 0
	v_cvt_pk_bf16_f32 v22, v22, v23
	v_cvt_pk_bf16_f32 v23, v24, v25
	ds_write_b64 v130, v[22:23] offset:2336
	v_lshlrev_b32_e32 v92, 16, v91
	v_and_b32_e32 v93, 0xffff0000, v91
	v_and_b32_e32 v91, 0xffff0000, v90
	v_lshlrev_b32_e32 v90, 16, v90
	v_pk_fma_f32 v[28:29], v[28:29], v[184:185], v[92:93]
	v_pk_fma_f32 v[26:27], v[26:27], v[182:183], v[90:91]
	s_nop 0
	v_cvt_pk_bf16_f32 v26, v26, v27
	v_cvt_pk_bf16_f32 v27, v28, v29
	ds_write_b64 v130, v[26:27] offset:2368
	v_lshlrev_b32_e32 v96, 16, v95
	v_and_b32_e32 v97, 0xffff0000, v95
	v_and_b32_e32 v95, 0xffff0000, v94
	v_lshlrev_b32_e32 v94, 16, v94
	v_pk_fma_f32 v[32:33], v[32:33], v[188:189], v[96:97]
	v_pk_fma_f32 v[30:31], v[30:31], v[186:187], v[94:95]
	s_nop 0
	v_cvt_pk_bf16_f32 v30, v30, v31
	v_cvt_pk_bf16_f32 v31, v32, v33
	ds_write_b64 v130, v[30:31] offset:2400
	v_lshlrev_b32_e32 v100, 16, v99
	v_and_b32_e32 v101, 0xffff0000, v99
	v_and_b32_e32 v99, 0xffff0000, v98
	v_lshlrev_b32_e32 v98, 16, v98
	v_pk_fma_f32 v[36:37], v[36:37], v[176:177], v[100:101]
	v_pk_fma_f32 v[34:35], v[34:35], v[174:175], v[98:99]
	s_nop 0
	v_cvt_pk_bf16_f32 v34, v34, v35
	v_cvt_pk_bf16_f32 v35, v36, v37
	ds_write_b64 v130, v[34:35] offset:4608
	v_lshlrev_b32_e32 v104, 16, v103
	v_and_b32_e32 v105, 0xffff0000, v103
	v_and_b32_e32 v103, 0xffff0000, v102
	v_lshlrev_b32_e32 v102, 16, v102
	v_pk_fma_f32 v[40:41], v[40:41], v[180:181], v[104:105]
	v_pk_fma_f32 v[38:39], v[38:39], v[178:179], v[102:103]
	s_nop 0
	v_cvt_pk_bf16_f32 v38, v38, v39
	v_cvt_pk_bf16_f32 v39, v40, v41
	ds_write_b64 v130, v[38:39] offset:4640
	v_lshlrev_b32_e32 v108, 16, v107
	v_and_b32_e32 v109, 0xffff0000, v107
	v_and_b32_e32 v107, 0xffff0000, v106
	v_lshlrev_b32_e32 v106, 16, v106
	v_pk_fma_f32 v[44:45], v[44:45], v[184:185], v[108:109]
	v_pk_fma_f32 v[42:43], v[42:43], v[182:183], v[106:107]
	s_nop 0
	v_cvt_pk_bf16_f32 v42, v42, v43
	v_cvt_pk_bf16_f32 v43, v44, v45
	ds_write_b64 v130, v[42:43] offset:4672
	v_lshlrev_b32_e32 v112, 16, v111
	v_and_b32_e32 v113, 0xffff0000, v111
	v_and_b32_e32 v111, 0xffff0000, v110
	v_lshlrev_b32_e32 v110, 16, v110
	v_pk_fma_f32 v[48:49], v[48:49], v[188:189], v[112:113]
	v_pk_fma_f32 v[46:47], v[46:47], v[186:187], v[110:111]
	s_nop 0
	v_cvt_pk_bf16_f32 v46, v46, v47
	v_cvt_pk_bf16_f32 v47, v48, v49
	ds_write_b64 v130, v[46:47] offset:4704
	v_lshlrev_b32_e32 v116, 16, v115
	v_and_b32_e32 v117, 0xffff0000, v115
	v_and_b32_e32 v115, 0xffff0000, v114
	v_lshlrev_b32_e32 v114, 16, v114
	v_pk_fma_f32 v[52:53], v[52:53], v[176:177], v[116:117]
	v_pk_fma_f32 v[50:51], v[50:51], v[174:175], v[114:115]
	s_nop 0
	v_cvt_pk_bf16_f32 v50, v50, v51
	v_cvt_pk_bf16_f32 v51, v52, v53
	ds_write_b64 v130, v[50:51] offset:6912
	v_lshlrev_b32_e32 v120, 16, v119
	v_and_b32_e32 v121, 0xffff0000, v119
	v_and_b32_e32 v119, 0xffff0000, v118
	v_lshlrev_b32_e32 v118, 16, v118
	v_pk_fma_f32 v[56:57], v[56:57], v[180:181], v[120:121]
	v_pk_fma_f32 v[54:55], v[54:55], v[178:179], v[118:119]
	s_nop 0
	v_cvt_pk_bf16_f32 v54, v54, v55
	v_cvt_pk_bf16_f32 v55, v56, v57
	ds_write_b64 v130, v[54:55] offset:6944
	v_lshlrev_b32_e32 v124, 16, v123
	v_and_b32_e32 v125, 0xffff0000, v123
	v_and_b32_e32 v123, 0xffff0000, v122
	v_lshlrev_b32_e32 v122, 16, v122
	v_pk_fma_f32 v[60:61], v[60:61], v[184:185], v[124:125]
	v_pk_fma_f32 v[58:59], v[58:59], v[182:183], v[122:123]
	s_nop 0
	v_cvt_pk_bf16_f32 v58, v58, v59
	v_cvt_pk_bf16_f32 v59, v60, v61
	ds_write_b64 v130, v[58:59] offset:6976
	v_lshlrev_b32_e32 v128, 16, v127
	v_and_b32_e32 v129, 0xffff0000, v127
	v_and_b32_e32 v127, 0xffff0000, v126
	v_lshlrev_b32_e32 v126, 16, v126
	v_pk_fma_f32 v[64:65], v[64:65], v[188:189], v[128:129]
	v_pk_fma_f32 v[62:63], v[62:63], v[186:187], v[126:127]
	s_nop 0
	v_cvt_pk_bf16_f32 v62, v62, v63
	v_cvt_pk_bf16_f32 v63, v64, v65
	ds_write_b64 v130, v[62:63] offset:7008
	s_waitcnt lgkmcnt(0)
	ds_read_b128 v[2:5], v131 offset:0
	ds_read_b128 v[6:9], v131 offset:1152
	ds_read_b128 v[10:13], v131 offset:2304
	ds_read_b128 v[14:17], v131 offset:3456
	ds_read_b128 v[18:21], v131 offset:4608
	ds_read_b128 v[22:25], v131 offset:5760
	ds_read_b128 v[26:29], v131 offset:6912
	ds_read_b128 v[30:33], v131 offset:8064
	s_waitcnt lgkmcnt(7)
	global_store_dwordx4 v132, v[2:5], s[74:75] sc1
	s_add_u32 s74, s74, 0x4000
	s_addc_u32 s75, s75, 0
	s_waitcnt lgkmcnt(6)
	global_store_dwordx4 v132, v[6:9], s[74:75] sc1
	s_add_u32 s74, s74, 0x4000
	s_addc_u32 s75, s75, 0
	s_waitcnt lgkmcnt(5)
	global_store_dwordx4 v132, v[10:13], s[74:75] sc1
	s_add_u32 s74, s74, 0x4000
	s_addc_u32 s75, s75, 0
	s_waitcnt lgkmcnt(4)
	global_store_dwordx4 v132, v[14:17], s[74:75] sc1
	s_add_u32 s74, s74, 0x4000
	s_addc_u32 s75, s75, 0
	s_waitcnt lgkmcnt(3)
	global_store_dwordx4 v132, v[18:21], s[74:75] sc1
	s_add_u32 s74, s74, 0x4000
	s_addc_u32 s75, s75, 0
	s_waitcnt lgkmcnt(2)
	global_store_dwordx4 v132, v[22:25], s[74:75] sc1
	s_add_u32 s74, s74, 0x4000
	s_addc_u32 s75, s75, 0
	s_waitcnt lgkmcnt(1)
	global_store_dwordx4 v132, v[26:29], s[74:75] sc1
	s_add_u32 s74, s74, 0x4000
	s_addc_u32 s75, s75, 0
	s_waitcnt lgkmcnt(0)
	global_store_dwordx4 v132, v[30:33], s[74:75] sc1
	s_waitcnt vmcnt(0)
	s_barrier
	s_cmp_lg_u32 s76, 0
	s_cbranch_scc1 .Ldn_noflag
	v_readlane_b32 s12, v253, 5
	v_readlane_b32 s13, v253, 6
	s_and_b32 s2, s78, 3
	s_or_b32 s2, s2, s77
	s_lshl_b32 s2, s2, 2
	v_mov_b32_e32 v170, s2
	v_mov_b32_e32 v171, 1
	s_nop 3
	s_mov_b64 exec, 1
	global_atomic_add v170, v171, s[12:13]
	s_mov_b64 exec, -1

.Lop_join:
	s_waitcnt vmcnt(0)
	s_nop 7
	s_barrier
	s_mul_i32 s12, s76, 9
	v_and_b32_e32 v170, 15, v1
	v_bfe_u32 v171, v1, 4, 2
	v_mul_u32_u24_e32 v130, 0x90, v170
	v_lshl_add_u32 v130, v171, 3, v130
	v_add_u32_e32 v130, s12, v130
	v_bfe_u32 v170, v1, 3, 3
	v_and_b32_e32 v171, 7, v1
	v_mul_u32_u24_e32 v131, 0x90, v170
	v_lshl_add_u32 v131, v171, 4, v131
	v_add_u32_e32 v131, s12, v131
	v_lshrrev_b32_e32 v172, 7, v1
	v_lshl_add_u32 v170, v172, 6, v170
	v_lshlrev_b32_e32 v132, 11, v170
	v_lshl_add_u32 v132, v171, 4, v132
	v_bfe_u32 v172, v1, 6, 1
	v_lshl_add_u32 v132, v172, 7, v132
	s_cmp_lg_u32 s82, 0
	s_cbranch_scc1 .Lop_cvbf
	v_pk_fma_f32 v[4:5], v[4:5], v[176:177], v[68:69]
	v_pk_fma_f32 v[2:3], v[2:3], v[174:175], v[66:67]
	s_nop 0
	v_cvt_pk_bf16_f32 v2, v2, v3
	v_cvt_pk_bf16_f32 v3, v4, v5
	ds_write_b64 v130, v[2:3] offset:0
	v_pk_fma_f32 v[8:9], v[8:9], v[180:181], v[72:73]
	v_pk_fma_f32 v[6:7], v[6:7], v[178:179], v[70:71]
	s_nop 0
	v_cvt_pk_bf16_f32 v6, v6, v7
	v_cvt_pk_bf16_f32 v7, v8, v9
	ds_write_b64 v130, v[6:7] offset:32
	v_pk_fma_f32 v[12:13], v[12:13], v[184:185], v[76:77]
	v_pk_fma_f32 v[10:11], v[10:11], v[182:183], v[74:75]
	s_nop 0
	v_cvt_pk_bf16_f32 v10, v10, v11
	v_cvt_pk_bf16_f32 v11, v12, v13
	ds_write_b64 v130, v[10:11] offset:64
	v_pk_fma_f32 v[16:17], v[16:17], v[188:189], v[80:81]
	v_pk_fma_f32 v[14:15], v[14:15], v[186:187], v[78:79]
	s_nop 0
	v_cvt_pk_bf16_f32 v14, v14, v15
	v_cvt_pk_bf16_f32 v15, v16, v17
	ds_write_b64 v130, v[14:15] offset:96
	v_pk_fma_f32 v[20:21], v[20:21], v[176:177], v[84:85]
	v_pk_fma_f32 v[18:19], v[18:19], v[174:175], v[82:83]
	s_nop 0
	v_cvt_pk_bf16_f32 v18, v18, v19
	v_cvt_pk_bf16_f32 v19, v20, v21
	ds_write_b64 v130, v[18:19] offset:2304
	v_pk_fma_f32 v[24:25], v[24:25], v[180:181], v[88:89]
	v_pk_fma_f32 v[22:23], v[22:23], v[178:179], v[86:87]
	s_nop 0
	v_cvt_pk_bf16_f32 v22, v22, v23
	v_cvt_pk_bf16_f32 v23, v24, v25
	ds_write_b64 v130, v[22:23] offset:2336
	v_pk_fma_f32 v[28:29], v[28:29], v[184:185], v[92:93]
	v_pk_fma_f32 v[26:27], v[26:27], v[182:183], v[90:91]
	s_nop 0
	v_cvt_pk_bf16_f32 v26, v26, v27
	v_cvt_pk_bf16_f32 v27, v28, v29
	ds_write_b64 v130, v[26:27] offset:2368
	v_pk_fma_f32 v[32:33], v[32:33], v[188:189], v[96:97]
	v_pk_fma_f32 v[30:31], v[30:31], v[186:187], v[94:95]
	s_nop 0
	v_cvt_pk_bf16_f32 v30, v30, v31
	v_cvt_pk_bf16_f32 v31, v32, v33
	ds_write_b64 v130, v[30:31] offset:2400
	v_pk_fma_f32 v[36:37], v[36:37], v[176:177], v[100:101]
	v_pk_fma_f32 v[34:35], v[34:35], v[174:175], v[98:99]
	s_nop 0
	v_cvt_pk_bf16_f32 v34, v34, v35
	v_cvt_pk_bf16_f32 v35, v36, v37
	ds_write_b64 v130, v[34:35] offset:4608
	v_pk_fma_f32 v[40:41], v[40:41], v[180:181], v[104:105]
	v_pk_fma_f32 v[38:39], v[38:39], v[178:179], v[102:103]
	s_nop 0
	v_cvt_pk_bf16_f32 v38, v38, v39
	v_cvt_pk_bf16_f32 v39, v40, v41
	ds_write_b64 v130, v[38:39] offset:4640
	v_pk_fma_f32 v[44:45], v[44:45], v[184:185], v[108:109]
	v_pk_fma_f32 v[42:43], v[42:43], v[182:183], v[106:107]
	s_nop 0
	v_cvt_pk_bf16_f32 v42, v42, v43
	v_cvt_pk_bf16_f32 v43, v44, v45
	ds_write_b64 v130, v[42:43] offset:4672
	v_pk_fma_f32 v[48:49], v[48:49], v[188:189], v[112:113]
	v_pk_fma_f32 v[46:47], v[46:47], v[186:187], v[110:111]
	s_nop 0
	v_cvt_pk_bf16_f32 v46, v46, v47
	v_cvt_pk_bf16_f32 v47, v48, v49
	ds_write_b64 v130, v[46:47] offset:4704
	v_pk_fma_f32 v[52:53], v[52:53], v[176:177], v[116:117]
	v_pk_fma_f32 v[50:51], v[50:51], v[174:175], v[114:115]
	s_nop 0
	v_cvt_pk_bf16_f32 v50, v50, v51
	v_cvt_pk_bf16_f32 v51, v52, v53
	ds_write_b64 v130, v[50:51] offset:6912
	v_pk_fma_f32 v[56:57], v[56:57], v[180:181], v[120:121]
	v_pk_fma_f32 v[54:55], v[54:55], v[178:179], v[118:119]
	s_nop 0
	v_cvt_pk_bf16_f32 v54, v54, v55
	v_cvt_pk_bf16_f32 v55, v56, v57
	ds_write_b64 v130, v[54:55] offset:6944
	v_pk_fma_f32 v[60:61], v[60:61], v[184:185], v[124:125]
	v_pk_fma_f32 v[58:59], v[58:59], v[182:183], v[122:123]
	s_nop 0
	v_cvt_pk_bf16_f32 v58, v58, v59
	v_cvt_pk_bf16_f32 v59, v60, v61
	ds_write_b64 v130, v[58:59] offset:6976
	v_pk_fma_f32 v[64:65], v[64:65], v[188:189], v[128:129]
	v_pk_fma_f32 v[62:63], v[62:63], v[186:187], v[126:127]
	s_nop 0
	v_cvt_pk_bf16_f32 v62, v62, v63
	v_cvt_pk_bf16_f32 v63, v64, v65
	ds_write_b64 v130, v[62:63] offset:7008
	s_branch .Lop_cvdone
.Lop_cvbf:
	v_lshlrev_b32_e32 v68, 16, v67
	v_and_b32_e32 v69, 0xffff0000, v67
	v_and_b32_e32 v67, 0xffff0000, v66
	v_lshlrev_b32_e32 v66, 16, v66
	v_pk_fma_f32 v[4:5], v[4:5], v[176:177], v[68:69]
	v_pk_fma_f32 v[2:3], v[2:3], v[174:175], v[66:67]
	s_nop 0
	v_cvt_pk_bf16_f32 v2, v2, v3
	v_cvt_pk_bf16_f32 v3, v4, v5
	ds_write_b64 v130, v[2:3] offset:0
	v_lshlrev_b32_e32 v72, 16, v71
	v_and_b32_e32 v73, 0xffff0000, v71
	v_and_b32_e32 v71, 0xffff0000, v70
	v_lshlrev_b32_e32 v70, 16, v70
	v_pk_fma_f32 v[8:9], v[8:9], v[180:181], v[72:73]
	v_pk_fma_f32 v[6:7], v[6:7], v[178:179], v[70:71]
	s_nop 0
	v_cvt_pk_bf16_f32 v6, v6, v7
	v_cvt_pk_bf16_f32 v7, v8, v9
	ds_write_b64 v130, v[6:7] offset:32
	v_lshlrev_b32_e32 v76, 16, v75
	v_and_b32_e32 v77, 0xffff0000, v75
	v_and_b32_e32 v75, 0xffff0000, v74
	v_lshlrev_b32_e32 v74, 16, v74
	v_pk_fma_f32 v[12:13], v[12:13], v[184:185], v[76:77]
	v_pk_fma_f32 v[10:11], v[10:11], v[182:183], v[74:75]
	s_nop 0
	v_cvt_pk_bf16_f32 v10, v10, v11
	v_cvt_pk_bf16_f32 v11, v12, v13
	ds_write_b64 v130, v[10:11] offset:64
	v_lshlrev_b32_e32 v80, 16, v79
	v_and_b32_e32 v81, 0xffff0000, v79
	v_and_b32_e32 v79, 0xffff0000, v78
	v_lshlrev_b32_e32 v78, 16, v78
	v_pk_fma_f32 v[16:17], v[16:17], v[188:189], v[80:81]
	v_pk_fma_f32 v[14:15], v[14:15], v[186:187], v[78:79]
	s_nop 0
	v_cvt_pk_bf16_f32 v14, v14, v15
	v_cvt_pk_bf16_f32 v15, v16, v17
	ds_write_b64 v130, v[14:15] offset:96
	v_lshlrev_b32_e32 v84, 16, v83
	v_and_b32_e32 v85, 0xffff0000, v83
	v_and_b32_e32 v83, 0xffff0000, v82
	v_lshlrev_b32_e32 v82, 16, v82
	v_pk_fma_f32 v[20:21], v[20:21], v[176:177], v[84:85]
	v_pk_fma_f32 v[18:19], v[18:19], v[174:175], v[82:83]
	s_nop 0
	v_cvt_pk_bf16_f32 v18, v18, v19
	v_cvt_pk_bf16_f32 v19, v20, v21
	ds_write_b64 v130, v[18:19] offset:2304
	v_lshlrev_b32_e32 v88, 16, v87
	v_and_b32_e32 v89, 0xffff0000, v87
	v_and_b32_e32 v87, 0xffff0000, v86
	v_lshlrev_b32_e32 v86, 16, v86
	v_pk_fma_f32 v[24:25], v[24:25], v[180:181], v[88:89]
	v_pk_fma_f32 v[22:23], v[22:23], v[178:179], v[86:87]
	s_nop 0
	v_cvt_pk_bf16_f32 v22, v22, v23
	v_cvt_pk_bf16_f32 v23, v24, v25
	ds_write_b64 v130, v[22:23] offset:2336
	v_lshlrev_b32_e32 v92, 16, v91
	v_and_b32_e32 v93, 0xffff0000, v91
	v_and_b32_e32 v91, 0xffff0000, v90
	v_lshlrev_b32_e32 v90, 16, v90
	v_pk_fma_f32 v[28:29], v[28:29], v[184:185], v[92:93]
	v_pk_fma_f32 v[26:27], v[26:27], v[182:183], v[90:91]
	s_nop 0
	v_cvt_pk_bf16_f32 v26, v26, v27
	v_cvt_pk_bf16_f32 v27, v28, v29
	ds_write_b64 v130, v[26:27] offset:2368
	v_lshlrev_b32_e32 v96, 16, v95
	v_and_b32_e32 v97, 0xffff0000, v95
	v_and_b32_e32 v95, 0xffff0000, v94
	v_lshlrev_b32_e32 v94, 16, v94
	v_pk_fma_f32 v[32:33], v[32:33], v[188:189], v[96:97]
	v_pk_fma_f32 v[30:31], v[30:31], v[186:187], v[94:95]
	s_nop 0
	v_cvt_pk_bf16_f32 v30, v30, v31
	v_cvt_pk_bf16_f32 v31, v32, v33
	ds_write_b64 v130, v[30:31] offset:2400
	v_lshlrev_b32_e32 v100, 16, v99
	v_and_b32_e32 v101, 0xffff0000, v99
	v_and_b32_e32 v99, 0xffff0000, v98
	v_lshlrev_b32_e32 v98, 16, v98
	v_pk_fma_f32 v[36:37], v[36:37], v[176:177], v[100:101]
	v_pk_fma_f32 v[34:35], v[34:35], v[174:175], v[98:99]
	s_nop 0
	v_cvt_pk_bf16_f32 v34, v34, v35
	v_cvt_pk_bf16_f32 v35, v36, v37
	ds_write_b64 v130, v[34:35] offset:4608
	v_lshlrev_b32_e32 v104, 16, v103
	v_and_b32_e32 v105, 0xffff0000, v103
	v_and_b32_e32 v103, 0xffff0000, v102
	v_lshlrev_b32_e32 v102, 16, v102
	v_pk_fma_f32 v[40:41], v[40:41], v[180:181], v[104:105]
	v_pk_fma_f32 v[38:39], v[38:39], v[178:179], v[102:103]
	s_nop 0
	v_cvt_pk_bf16_f32 v38, v38, v39
	v_cvt_pk_bf16_f32 v39, v40, v41
	ds_write_b64 v130, v[38:39] offset:4640
	v_lshlrev_b32_e32 v108, 16, v107
	v_and_b32_e32 v109, 0xffff0000, v107
	v_and_b32_e32 v107, 0xffff0000, v106
	v_lshlrev_b32_e32 v106, 16, v106
	v_pk_fma_f32 v[44:45], v[44:45], v[184:185], v[108:109]
	v_pk_fma_f32 v[42:43], v[42:43], v[182:183], v[106:107]
	s_nop 0
	v_cvt_pk_bf16_f32 v42, v42, v43
	v_cvt_pk_bf16_f32 v43, v44, v45
	ds_write_b64 v130, v[42:43] offset:4672
	v_lshlrev_b32_e32 v112, 16, v111
	v_and_b32_e32 v113, 0xffff0000, v111
	v_and_b32_e32 v111, 0xffff0000, v110
	v_lshlrev_b32_e32 v110, 16, v110
	v_pk_fma_f32 v[48:49], v[48:49], v[188:189], v[112:113]
	v_pk_fma_f32 v[46:47], v[46:47], v[186:187], v[110:111]
	s_nop 0
	v_cvt_pk_bf16_f32 v46, v46, v47
	v_cvt_pk_bf16_f32 v47, v48, v49
	ds_write_b64 v130, v[46:47] offset:4704
	v_lshlrev_b32_e32 v116, 16, v115
	v_and_b32_e32 v117, 0xffff0000, v115
	v_and_b32_e32 v115, 0xffff0000, v114
	v_lshlrev_b32_e32 v114, 16, v114
	v_pk_fma_f32 v[52:53], v[52:53], v[176:177], v[116:117]
	v_pk_fma_f32 v[50:51], v[50:51], v[174:175], v[114:115]
	s_nop 0
	v_cvt_pk_bf16_f32 v50, v50, v51
	v_cvt_pk_bf16_f32 v51, v52, v53
	ds_write_b64 v130, v[50:51] offset:6912
	v_lshlrev_b32_e32 v120, 16, v119
	v_and_b32_e32 v121, 0xffff0000, v119
	v_and_b32_e32 v119, 0xffff0000, v118
	v_lshlrev_b32_e32 v118, 16, v118
	v_pk_fma_f32 v[56:57], v[56:57], v[180:181], v[120:121]
	v_pk_fma_f32 v[54:55], v[54:55], v[178:179], v[118:119]
	s_nop 0
	v_cvt_pk_bf16_f32 v54, v54, v55
	v_cvt_pk_bf16_f32 v55, v56, v57
	ds_write_b64 v130, v[54:55] offset:6944
	v_lshlrev_b32_e32 v124, 16, v123
	v_and_b32_e32 v125, 0xffff0000, v123
	v_and_b32_e32 v123, 0xffff0000, v122
	v_lshlrev_b32_e32 v122, 16, v122
	v_pk_fma_f32 v[60:61], v[60:61], v[184:185], v[124:125]
	v_pk_fma_f32 v[58:59], v[58:59], v[182:183], v[122:123]
	s_nop 0
	v_cvt_pk_bf16_f32 v58, v58, v59
	v_cvt_pk_bf16_f32 v59, v60, v61
	ds_write_b64 v130, v[58:59] offset:6976
	v_lshlrev_b32_e32 v128, 16, v127
	v_and_b32_e32 v129, 0xffff0000, v127
	v_and_b32_e32 v127, 0xffff0000, v126
	v_lshlrev_b32_e32 v126, 16, v126
	v_pk_fma_f32 v[64:65], v[64:65], v[188:189], v[128:129]
	v_pk_fma_f32 v[62:63], v[62:63], v[186:187], v[126:127]
	s_nop 0
	v_cvt_pk_bf16_f32 v62, v62, v63
	v_cvt_pk_bf16_f32 v63, v64, v65
	ds_write_b64 v130, v[62:63] offset:7008
.Lop_cvdone:
	s_waitcnt lgkmcnt(0)
	ds_read_b128 v[2:5], v131 offset:0
	ds_read_b128 v[6:9], v131 offset:1152
	ds_read_b128 v[10:13], v131 offset:2304
	ds_read_b128 v[14:17], v131 offset:3456
	ds_read_b128 v[18:21], v131 offset:4608
	ds_read_b128 v[22:25], v131 offset:5760
	ds_read_b128 v[26:29], v131 offset:6912
	ds_read_b128 v[30:33], v131 offset:8064
	s_waitcnt lgkmcnt(7)
	global_store_dwordx4 v132, v[2:5], s[74:75] sc1
	s_add_u32 s74, s74, 0x4000
	s_addc_u32 s75, s75, 0
	s_waitcnt lgkmcnt(6)
	global_store_dwordx4 v132, v[6:9], s[74:75] sc1
	s_add_u32 s74, s74, 0x4000
	s_addc_u32 s75, s75, 0
	s_waitcnt lgkmcnt(5)
	global_store_dwordx4 v132, v[10:13], s[74:75] sc1
	s_add_u32 s74, s74, 0x4000
	s_addc_u32 s75, s75, 0
	s_waitcnt lgkmcnt(4)
	global_store_dwordx4 v132, v[14:17], s[74:75] sc1
	s_add_u32 s74, s74, 0x4000
	s_addc_u32 s75, s75, 0
	s_waitcnt lgkmcnt(3)
	global_store_dwordx4 v132, v[18:21], s[74:75] sc1
	s_add_u32 s74, s74, 0x4000
	s_addc_u32 s75, s75, 0
	s_waitcnt lgkmcnt(2)
	global_store_dwordx4 v132, v[22:25], s[74:75] sc1
	s_add_u32 s74, s74, 0x4000
	s_addc_u32 s75, s75, 0
	s_waitcnt lgkmcnt(1)
	global_store_dwordx4 v132, v[26:29], s[74:75] sc1
	s_add_u32 s74, s74, 0x4000
	s_addc_u32 s75, s75, 0
	s_waitcnt lgkmcnt(0)
	global_store_dwordx4 v132, v[30:33], s[74:75] sc1
	s_waitcnt vmcnt(0)
	s_barrier
	s_cmp_lg_u32 s76, 0
	s_cbranch_scc1 .Lop_noflag
	v_readlane_b32 s12, v253, 5
	v_readlane_b32 s13, v253, 6
	s_and_b32 s2, s78, 3
	s_or_b32 s2, s2, s77
	s_lshl_b32 s2, s2, 2
	v_mov_b32_e32 v170, s2
	v_mov_b32_e32 v171, 1
	s_nop 3
	s_mov_b64 exec, 1
	global_atomic_add v170, v171, s[12:13]
	s_mov_b64 exec, -1

.LBB0_727:
	s_mov_b64 s[2:3], s[46:47]
	s_add_i32 s18, s2, 1
	s_cmp_ge_i32 s18, s3
	v_readlane_b32 s30, v254, 6
	v_readlane_b32 s38, v254, 8
	v_readlane_b32 s56, v254, 22
	v_readlane_b32 s31, v254, 7
	v_readlane_b32 s39, v254, 9
	v_readlane_b32 s57, v254, 23
	s_cbranch_scc1 .LBB0_781
	s_cmp_eq_u32 s2, 5
	s_cbranch_scc1 .LBB0_781
	s_cmp_eq_u32 s2, 14
	s_cbranch_scc1 .LBB0_781
	s_cmp_eq_u32 s2, 9
	s_cbranch_scc1 .LBB0_781
	s_cmp_eq_u32 s2, 18
	s_cbranch_scc1 .LBB0_781
	s_waitcnt vmcnt(0)
	s_waitcnt lgkmcnt(0)
	s_barrier
	s_mov_b64 s[2:3], exec
	v_readlane_b32 s4, v253, 7
	v_readlane_b32 s5, v253, 8
	s_and_b64 s[4:5], s[2:3], s[4:5]
	s_mov_b64 exec, s[4:5]
	s_cbranch_execz .LBB0_780
	s_add_i32 s13, 0, 0x24000
	s_mov_b64 s[4:5], src_shared_base
	s_cmp_lg_u32 s13, -1
	s_cselect_b32 s4, s13, 0
	s_cselect_b32 s6, s5, 0
	s_add_i32 s12, 0, 0x24004
	s_cmp_lg_u32 s12, -1
	v_mov_b32_e32 v2, s4
	v_mov_b32_e32 v3, s6
	s_cselect_b32 s4, s12, 0
	s_cselect_b32 s5, s5, 0
	s_waitcnt vmcnt(0) expcnt(0) lgkmcnt(0)
	s_and_b32 s4, s101, 0xffff
	v_mov_b32_e32 v4, s4
	v_mov_b32_e32 v2, s4
	v_mov_b32_e32 v3, s5
	s_lshr_b32 s4, s101, 16
	v_mov_b32_e32 v2, s4
	s_waitcnt vmcnt(0) lgkmcnt(0)
	v_cmp_eq_u32_e32 vcc, 0, v4
	s_and_saveexec_b64 s[4:5], vcc
	s_cbranch_execz .LBB0_744
	s_mov_b32 s14, 1
	s_branch .LBB0_732
